# A2 loop: q blocks 0,1 held in the freed staging VGPRs instead of re-read from LDS every tile
# baseline (speedup 1.0000x reference)
; #define PHON(k) constexpr (((MK_PHMASK) >> (k)) & 1)
; __device__ __forceinline__ int lane_id_v() { int l; asm volatile("v_mbcnt_lo_u32_b32 %0, -1, 0\n\tv_mbcnt_hi_u32_b32 %0, -1, %0" : "=v"(l)); return l; }
; __device__ __forceinline__ void attn_unit_A2(const bf16_t* __restrict__ Qb, int ldq, const bf16_t* __restrict__ Kh, int ldk, const bf16_t* __restrict__ Vh, int ldv, int nkeys, int q0, ...
;   constexpr int ROWB = 256, SHM_K = 64 * ROWB;
;   int tid_ = wave0 * 64 + lane_id_v();
;   const int tid = tid_, wid = tid >> 6, lane = tid & 63, r32 = lane & 31, hi = lane >> 5;
;   char* V_lds = lds; char* K_lds = lds + LDS_K_OFF;
;   float* ws = (float*)(lds + LDS_WS_OFF) + wid * 64; float* sl0 = ws; float* sl1 = ws + 32;
;   float* tbl_l = (float*)(lds + LDS_TBL_OFF);
;   char* qls = lds + LDS_Q_OFF + wid * 8192 + lane * 16;
;   __syncthreads();
;   for (int i = tid; i < TBLN; i += 512) tbl_l[i] = tblg[i];
;   { const bf16_t* Qw = Qb + (long)(wid * QBLK + r32) * ldq + hi * 8;
; #pragma unroll
;     for (int i = 0; i < 8; ++i) *reinterpret_cast<bf16x8*>(qls + i * 1024) = *reinterpret_cast<const bf16x8*>(Qw + i * 16); }
;   float m0 = -1e30f, m1 = -1e30f, l0 = 0.f, l1 = 0.f; f32x16 oa[4] = {}, ob[4] = {};
;   const int sr = tid >> 4, sc = (tid & 15) * 8, vst0 = v_st(sr, sc), vst1 = v_st(32 + sr, sc);
;   const int vb0 = (int)(uintptr_t)V_lds + v_rd_base(lane);
;   const int qlane = q0 + wid * QBLK + r32;
;   bf16x8 vs0, vs1, ks0, ks1;
;     ...
;   const int NT = nkeys / KVBLK;
;   const int kbA = (int)(uintptr_t)K_lds + r32 * 256 + (((r32 & 15) << 4) ^ (hi << 4)), qaA = (int)(uintptr_t)qls;
;   SLOAD2(0); asm volatile("s_waitcnt vmcnt(0)" ::: "memory"); SWRITE2(0); __syncthreads();
; __global__ void __launch_bounds__(512, 2) mega_fwd(Args args) {
;     ...
;             if PHON(6) for (int u = bid; u < 256; u += G) { const int xq = u & 7, hd = xq & 3, qb = (u >> 3) + 32 * (xq >> 2), q0 = qb * 256;
;                 { const float cb_lo = rel_bias[15 * 8 + hd] * L2E, cb_hi = rel_bias[31 * 8 + hd] * L2E;
;                   att::attn_unit_A2(PROJ + (size_t)q0 * LDP + C_AQ + hd * 128, LDP, PROJ + C_AK + hd * 128, LDP, PROJ + C_AV + hd * 128, LDP, S, q0,
;                                     TBLA + hd * TBLN, cb_lo, cb_hi, MIX + (size_t)q0 * DM + hd * 128, DM, lam, diff_subln + l * 128, 1.0f - lam_init, (char*)lds, wave0); }
.LBB0_334:
	s_or_b64 exec, exec, s[4:5]
	s_lshl_b32 s4, s57, 8
	s_and_b32 s7, s4, 0x2000
	s_lshl_b32 s4, s59, 3
	s_ashr_i32 s23, s59, 3
	s_and_b32 s4, s4, 32
	s_add_i32 s4, s4, s23
	s_lshl_b32 s6, s20, 8
	s_lshl_b32 s20, s4, 8
	s_ashr_i32 s21, s20, 31
	s_mul_i32 s4, s4, 0x280000
	s_mul_hi_i32 s5, s20, 0x2800
	s_add_u32 s4, s24, s4
	s_addc_u32 s5, s25, s5
	s_lshl_b32 s10, s22, 7
	s_lshl_b32 s8, s22, 8
	v_ashrrev_i32_e32 v3, 6, v2
	s_add_u32 s4, s4, s8
	s_addc_u32 s5, s5, 0
	v_and_b32_e32 v46, 31, v6
	v_lshlrev_b32_e32 v196, 5, v3
	v_or_b32_e32 v0, v196, v46
	v_mov_b64_e32 v[4:5], s[4:5]
	v_mad_i64_i32 v[4:5], s[4:5], v0, s55, v[4:5]
	v_and_b32_e32 v9, 63, v6
	s_add_u32 s4, s26, s8
	v_lshrrev_b32_e32 v47, 5, v9
	s_addc_u32 s5, s27, 0
	v_lshlrev_b32_e32 v0, 4, v47
	s_add_u32 s8, s45, s8
	v_lshl_add_u64 v[4:5], v[4:5], 0, v[0:1]
	s_addc_u32 s9, s46, 0
	v_lshlrev_b32_e32 v49, 3, v6
	global_load_dwordx4 v[10:13], v[4:5], off
	global_load_dwordx4 v[14:17], v[4:5], off offset:32
	global_load_dwordx4 v[18:21], v[4:5], off offset:64
	global_load_dwordx4 v[22:25], v[4:5], off offset:96
	global_load_dwordx4 v[26:29], v[4:5], off offset:128
	global_load_dwordx4 v[30:33], v[4:5], off offset:160
	global_load_dwordx4 v[34:37], v[4:5], off offset:192
	global_load_dwordx4 v[38:41], v[4:5], off offset:224
	v_ashrrev_i32_e32 v48, 4, v2
	v_and_b32_e32 v4, 0x78, v49
	v_mov_b64_e32 v[42:43], s[8:9]
	v_lshlrev_b32_e32 v4, 1, v4
	v_add_u32_e32 v50, 32, v48
	v_mad_i64_i32 v[44:45], s[8:9], v48, s55, v[42:43]
	v_mov_b32_e32 v5, v1
	v_lshl_add_u64 v[44:45], v[44:45], 0, v[4:5]
	v_mad_i64_i32 v[42:43], s[8:9], v50, s55, v[42:43]
	global_load_dwordx4 v[176:179], v[44:45], off
	v_lshl_add_u64 v[42:43], v[42:43], 0, v[4:5]
	global_load_dwordx4 v[180:183], v[42:43], off
	v_mov_b64_e32 v[42:43], s[4:5]
	v_mad_i64_i32 v[44:45], s[4:5], v48, s55, v[42:43]
	v_lshl_add_u64 v[44:45], v[44:45], 0, v[4:5]
	global_load_dwordx4 v[184:187], v[44:45], off
	v_mad_i64_i32 v[42:43], s[4:5], v50, s55, v[42:43]
	v_lshl_add_u64 v[42:43], v[42:43], 0, v[4:5]
	global_load_dwordx4 v[188:191], v[42:43], off
	s_waitcnt vmcnt(13)
	v_mul_f32_e32 v197, 0x3fb8aa3b, v7
	s_waitcnt vmcnt(12)
	v_mul_f32_e32 v207, 0x3fb8aa3b, v8
	v_lshlrev_b32_e32 v3, 13, v3
	v_lshlrev_b32_e32 v7, 4, v9
	v_and_b32_e32 v8, 0xfffff0, v48
	v_lshlrev_b32_e32 v42, 1, v48
	v_readlane_b32 s4, v254, 58
	v_lshrrev_b32_e32 v43, 1, v48
	v_bfe_u32 v44, v49, 5, 2
	v_add3_u32 v208, s4, v3, v7
	v_and_or_b32 v3, v48, 8, v8
	v_and_b32_e32 v45, 3, v48
	v_lshrrev_b32_e32 v3, 1, v3
	v_and_or_b32 v8, v48, 4, v45
	v_or_b32_e32 v3, v3, v44
	v_and_b32_e32 v5, 0x3fffffc0, v2
	v_lshlrev_b32_e32 v8, 6, v8
	v_and_b32_e32 v42, 48, v4
	v_lshlrev_b32_e32 v3, 9, v3
	s_add_i32 s37, 0, 0x14000
	v_or3_b32 v209, v3, v8, v42
	v_lshl_add_u32 v201, v5, 2, s37
	v_and_b32_e32 v3, 0xfffff0, v50
	v_lshlrev_b32_e32 v5, 1, v50
	v_and_or_b32 v3, v50, 8, v3
	v_lshrrev_b32_e32 v3, 1, v3
	v_or_b32_e32 v3, v3, v44
	v_lshlrev_b32_e32 v3, 9, v3
	v_or3_b32 v210, v3, v8, v42
	v_and_b32_e32 v2, 0xf0, v2
	s_add_i32 s44, 0, 0x8000
	v_and_b32_e32 v8, 0xc0, v7
	v_lshlrev_b32_e32 v7, 1, v9
	s_cmp_lg_u32 s44, -1
	s_cselect_b32 s4, s44, 0
	s_add_i32 s60, s20, 0x4ff
	s_waitcnt vmcnt(11)
	ds_write_b128 v208, v[10:13]
	s_waitcnt vmcnt(10)
	ds_write_b128 v208, v[14:17] offset:1024
	s_waitcnt vmcnt(9)
	ds_write_b128 v208, v[18:21] offset:2048
	s_waitcnt vmcnt(8)
	ds_write_b128 v208, v[22:25] offset:3072
	s_waitcnt vmcnt(7)
	ds_write_b128 v208, v[26:29] offset:4096
	s_waitcnt vmcnt(6)
	ds_write_b128 v208, v[30:33] offset:5120
	s_waitcnt vmcnt(5)
	ds_write_b128 v208, v[34:37] offset:6144
	s_waitcnt vmcnt(4)
	ds_write_b128 v208, v[38:41] offset:7168
	v_add_u32_e32 v12, 0, v209
	s_waitcnt vmcnt(0)
	v_and_b32_e32 v11, 15, v6
	v_bitop3_b32 v6, v47, v6, 15 bitop3:0x78
	v_and_b32_e32 v10, 32, v7
	v_lshlrev_b32_e32 v7, 8, v46
	v_lshlrev_b32_e32 v6, 4, v6
	v_lshlrev_b32_e32 v3, 3, v9
	v_add3_u32 v211, v7, s4, v6
	v_mad_i64_i32 v[6:7], s[4:5], v48, s55, 0
	s_waitcnt vmcnt(3)
	ds_write_b128 v12, v[176:179]
	v_add_u32_e32 v12, 0, v210
	s_waitcnt vmcnt(2)
	ds_write_b128 v12, v[180:183]
	v_lshlrev_b32_e32 v12, 8, v48
	v_bitop3_b32 v212, v4, v12, v2 bitop3:0xde
	v_add_u32_e32 v12, 0, v212
	s_cmp_lg_u32 0, -1
	s_waitcnt vmcnt(1)
	ds_write_b128 v12, v[184:187] offset:32768
	v_lshlrev_b32_e32 v12, 8, v50
	v_bitop3_b32 v213, v12, v4, v2 bitop3:0xf6
	v_and_b32_e32 v5, 24, v3
	v_add_u32_e32 v2, 0, v213
	s_cselect_b32 s4, 0, 0
	s_lshl_b32 s8, s23, 8
	v_and_b32_e32 v3, 0x100, v3
	s_waitcnt vmcnt(0)
; __device__ __forceinline__ int v_st(int k, int c) { const int kk = (k & ~0xC) | ((k & 4) << 1) | ((k & 8) >> 1); return ((kk >> 3) * 4 + (c >> 5)) * 512 + ((kk & 7) * 32 + (c & 31)) * 2; }
; __device__ __forceinline__ int v_rd_base(int lane) { return ((lane & 3) << 3) | (((lane >> 2) & 3) << 6) | (((lane >> 4) & 1) << 5) | (((lane >> 5) & 1) << 8); }
; #define SLOAD2(k0) do { vs0 = *reinterpret_cast<const bf16x8*>(&Vh[(long)((k0) + sr) * ldv + sc]); vs1 = *reinterpret_cast<const bf16x8*>(&Vh[(long)((k0) + 32 + sr) * ldv + sc]); \
;     ks0 = *reinterpret_cast<const bf16x8*>(&Kh[(long)((k0) + sr) * ldk + sc]); ks1 = *reinterpret_cast<const bf16x8*>(&Kh[(long)((k0) + 32 + sr) * ldk + sc]); } while (0)
; #define SWRITE2(b) do { *(bf16x8*)(V_lds + (b) * SHM_V + vst0) = vs0; *(bf16x8*)(V_lds + (b) * SHM_V + vst1) = vs1; \
;     *(bf16x8*)(K_lds + (b) * SHM_K + KSWZ(sr, sc * 2)) = ks0; *(bf16x8*)(K_lds + (b) * SHM_K + KSWZ(32 + sr, sc * 2)) = ks1; } while (0)
; __device__ __forceinline__ void attn_unit_A2(const bf16_t* __restrict__ Qb, int ldq, const bf16_t* __restrict__ Kh, int ldk, const bf16_t* __restrict__ Vh, int ldv, int nkeys, int q0, ...
;     ...
;   float m0 = -1e30f, m1 = -1e30f, l0 = 0.f, l1 = 0.f; f32x16 oa[4] = {}, ob[4] = {};
;   const int sr = tid >> 4, sc = (tid & 15) * 8, vst0 = v_st(sr, sc), vst1 = v_st(32 + sr, sc);
;   const int vb0 = (int)(uintptr_t)V_lds + v_rd_base(lane);
;   const int qlane = q0 + wid * QBLK + r32;
;   bf16x8 vs0, vs1, ks0, ks1;
;     ...
;   const int NT = nkeys / KVBLK;
;   const int kbA = (int)(uintptr_t)K_lds + r32 * 256 + (((r32 & 15) << 4) ^ (hi << 4)), qaA = (int)(uintptr_t)qls;
;   SLOAD2(0); asm volatile("s_waitcnt vmcnt(0)" ::: "memory"); SWRITE2(0); __syncthreads();
	ds_write_b128 v2, v[188:191] offset:32768
	v_add3_u32 v2, v8, s4, v5
	s_add_i32 s7, s7, s8
	v_add3_u32 v214, v2, v10, v3
	v_add_u32_e32 v2, s7, v196
	v_or_b32_e32 v2, v2, v46
	v_lshlrev_b32_e32 v2, 2, v2
	v_add_u32_e32 v216, v201, v0
	v_sub_u32_e32 v0, v0, v2
	v_add_u32_e32 v217, 0, v0
	v_lshlrev_b32_e32 v0, 4, v11
	v_or3_b32 v6, v6, s6, v0
	v_mov_b32_e32 v14, v1
	v_mov_b32_e32 v15, v1
	v_cmp_gt_u32_e64 s[4:5], 32, v9
	v_lshl_add_u32 v215, v46, 2, v201
	v_lshl_add_u64 v[198:199], s[18:19], 0, v[6:7]
	v_mov_b32_e32 v0, v1
	v_mov_b32_e32 v2, v1
	v_mov_b32_e32 v3, v1
	v_mov_b32_e32 v4, v1
	v_mov_b32_e32 v5, v1
	v_mov_b32_e32 v6, v1
	v_mov_b32_e32 v7, v1
	v_mov_b32_e32 v8, v1
	v_mov_b32_e32 v9, v1
	v_mov_b32_e32 v10, v1
	v_mov_b32_e32 v11, v1
	v_mov_b32_e32 v12, v1
	v_mov_b32_e32 v13, v1
	v_mov_b64_e32 v[46:47], v[14:15]
	v_mov_b64_e32 v[30:31], v[14:15]
	v_mov_b64_e32 v[78:79], v[14:15]
	v_mov_b64_e32 v[126:127], v[14:15]
	v_mov_b64_e32 v[142:143], v[14:15]
	v_mov_b64_e32 v[110:111], v[14:15]
	v_mov_b64_e32 v[62:63], v[14:15]
	v_mov_b64_e32 v[94:95], v[14:15]
	s_mov_b32 s11, 0
	s_sub_i32 s61, 0, s7
	v_mov_b32_e32 v218, 0xc3480000
	v_mov_b32_e32 v219, 0
	s_mov_b32 s62, 0
	s_mov_b32 s63, 0
	v_mov_b64_e32 v[44:45], v[12:13]
	v_mov_b64_e32 v[42:43], v[10:11]
	v_mov_b64_e32 v[40:41], v[8:9]
	v_mov_b64_e32 v[38:39], v[6:7]
	v_mov_b64_e32 v[36:37], v[4:5]
	v_mov_b64_e32 v[34:35], v[2:3]
	v_mov_b64_e32 v[32:33], v[0:1]
	v_mov_b64_e32 v[28:29], v[12:13]
	v_mov_b64_e32 v[26:27], v[10:11]
	v_mov_b64_e32 v[24:25], v[8:9]
	v_mov_b64_e32 v[22:23], v[6:7]
	v_mov_b64_e32 v[20:21], v[4:5]
	v_mov_b64_e32 v[18:19], v[2:3]
	v_mov_b64_e32 v[16:17], v[0:1]
	v_mov_b64_e32 v[76:77], v[12:13]
	v_mov_b64_e32 v[74:75], v[10:11]
	v_mov_b64_e32 v[72:73], v[8:9]
	v_mov_b64_e32 v[70:71], v[6:7]
	v_mov_b64_e32 v[68:69], v[4:5]
	v_mov_b64_e32 v[66:67], v[2:3]
	v_mov_b64_e32 v[64:65], v[0:1]
	v_mov_b64_e32 v[124:125], v[12:13]
	v_mov_b64_e32 v[122:123], v[10:11]
	v_mov_b64_e32 v[120:121], v[8:9]
	v_mov_b64_e32 v[118:119], v[6:7]
	v_mov_b64_e32 v[116:117], v[4:5]
	v_mov_b64_e32 v[114:115], v[2:3]
	v_mov_b64_e32 v[112:113], v[0:1]
	v_mov_b64_e32 v[140:141], v[12:13]
	v_mov_b64_e32 v[138:139], v[10:11]
	v_mov_b64_e32 v[136:137], v[8:9]
	v_mov_b64_e32 v[134:135], v[6:7]
	v_mov_b64_e32 v[132:133], v[4:5]
	v_mov_b64_e32 v[130:131], v[2:3]
	v_mov_b64_e32 v[128:129], v[0:1]
	v_mov_b64_e32 v[108:109], v[12:13]
	v_mov_b64_e32 v[106:107], v[10:11]
	v_mov_b64_e32 v[104:105], v[8:9]
	v_mov_b64_e32 v[102:103], v[6:7]
	v_mov_b64_e32 v[100:101], v[4:5]
	v_mov_b64_e32 v[98:99], v[2:3]
	v_mov_b64_e32 v[96:97], v[0:1]
	v_mov_b64_e32 v[60:61], v[12:13]
	v_mov_b64_e32 v[58:59], v[10:11]
	v_mov_b64_e32 v[56:57], v[8:9]
	v_mov_b64_e32 v[54:55], v[6:7]
	v_mov_b64_e32 v[52:53], v[4:5]
	v_mov_b64_e32 v[50:51], v[2:3]
	v_mov_b64_e32 v[48:49], v[0:1]
	v_mov_b64_e32 v[92:93], v[12:13]
	v_mov_b64_e32 v[90:91], v[10:11]
	v_mov_b64_e32 v[88:89], v[8:9]
	v_mov_b64_e32 v[86:87], v[6:7]
	v_mov_b64_e32 v[84:85], v[4:5]
	v_mov_b64_e32 v[82:83], v[2:3]
	v_mov_b64_e32 v[80:81], v[0:1]
	v_mov_b32_e32 v14, 0
	v_mov_b32_e32 v0, 0xc3480000
	v_mbcnt_lo_u32_b32 v184, -1, 0
	v_mbcnt_hi_u32_b32 v184, -1, v184
	v_readlane_b32 s6, v254, 8
	s_nop 1
	v_add_u32_e32 v184, s6, v184
	v_lshrrev_b32_e32 v185, 4, v184
	v_and_b32_e32 v186, 15, v184
	v_and_b32_e32 v187, 15, v185
	v_xor_b32_e32 v187, v186, v187
	v_sub_u32_e32 v187, v187, v186
	v_lshlrev_b32_e32 v187, 4, v187
	v_add_u32_e32 v187, 0xfffafc00, v187
	v_add_co_u32_e32 v180, vcc, v187, v198
	s_nop 1
	v_addc_co_u32_e32 v181, vcc, -1, v199, vcc
	v_add_co_u32_e32 v182, vcc, 0x50000, v180
	s_nop 1
	v_addc_co_u32_e32 v183, vcc, 0, v181, vcc
	v_lshrrev_b32_e32 v187, 7, v184
	v_lshlrev_b32_e32 v187, 3, v187
	v_bfe_u32 v188, v184, 2, 3
	v_add_u32_e32 v187, v187, v188
	v_sub_u32_e32 v187, v187, v185
	v_mul_i32_i24_e32 v187, 0x2800, v187
	v_bfe_u32 v188, v184, 5, 2
	v_lshlrev_b32_e32 v188, 6, v188
	v_and_b32_e32 v189, 3, v184
	v_lshl_add_u32 v188, v189, 4, v188
	v_lshlrev_b32_e32 v186, 4, v186
	v_sub_u32_e32 v188, v188, v186
	v_add_u32_e32 v187, v187, v188
	v_add_u32_e32 v187, 0xfffb0000, v187
	v_add_co_u32_e32 v176, vcc, v187, v198
	s_nop 1
	v_addc_co_u32_e32 v177, vcc, -1, v199, vcc
	v_add_co_u32_e32 v178, vcc, 0x50000, v176
	s_nop 1
	v_addc_co_u32_e32 v179, vcc, 0, v177, vcc
	ds_read_b128 v[184:187], v208 offset:0
	ds_read_b128 v[188:191], v208 offset:0x400
	s_waitcnt lgkmcnt(0)
	s_barrier
; template <int M>
; __device__ __forceinline__ void qkt_map_roll(f32x16& p0, f32x16& p1, int kb, int qa) {
;   p0 = f32x16{}; p1 = f32x16{};
;   const int a0 = kb ^ ((M << 7) | (0 << 5)); const bf16x8 x0 = lds_rd128<0>(a0), y0 = lds_rd128<8192>(a0); const bf16x8 z0 = (M == 0) ? lds_rd128<0>(qa) : lds_rd128<4096>(qa);
;   const int a1 = kb ^ ((M << 7) | (1 << 5)); const bf16x8 x1 = lds_rd128<0>(a1), y1 = lds_rd128<8192>(a1); const bf16x8 z1 = (M == 0) ? lds_rd128<1024>(qa) : lds_rd128<5120>(qa);
;   asm volatile("s_waitcnt lgkmcnt(3)" ::: "memory"); SBAR();
;   p0 = __builtin_amdgcn_mfma_f32_32x32x16_bf16(x0, z0, p0, 0, 0, 0); p1 = __builtin_amdgcn_mfma_f32_32x32x16_bf16(y0, z0, p1, 0, 0, 0);
;   const int a2 = kb ^ ((M << 7) | (2 << 5)); const bf16x8 x2 = lds_rd128<0>(a2), y2 = lds_rd128<8192>(a2); const bf16x8 z2 = (M == 0) ? lds_rd128<2048>(qa) : lds_rd128<6144>(qa);
;   asm volatile("s_waitcnt lgkmcnt(3)" ::: "memory"); SBAR();
;   p0 = __builtin_amdgcn_mfma_f32_32x32x16_bf16(x1, z1, p0, 0, 0, 0); p1 = __builtin_amdgcn_mfma_f32_32x32x16_bf16(y1, z1, p1, 0, 0, 0);
;   const int a3 = kb ^ ((M << 7) | (3 << 5)); const bf16x8 x3 = lds_rd128<0>(a3), y3 = lds_rd128<8192>(a3); const bf16x8 z3 = (M == 0) ? lds_rd128<3072>(qa) : lds_rd128<7168>(qa);
;   asm volatile("s_waitcnt lgkmcnt(3)" ::: "memory"); SBAR();
;   p0 = __builtin_amdgcn_mfma_f32_32x32x16_bf16(x2, z2, p0, 0, 0, 0); p1 = __builtin_amdgcn_mfma_f32_32x32x16_bf16(y2, z2, p1, 0, 0, 0);
;   asm volatile("s_waitcnt lgkmcnt(0)" ::: "memory"); SBAR();
;   p0 = __builtin_amdgcn_mfma_f32_32x32x16_bf16(x3, z3, p0, 0, 0, 0); p1 = __builtin_amdgcn_mfma_f32_32x32x16_bf16(y3, z3, p1, 0, 0, 0);
;   SBAR();
; }
; __device__ __forceinline__ void attn_unit_A2(const bf16_t* __restrict__ Qb, int ldq, const bf16_t* __restrict__ Kh, int ldk, const bf16_t* __restrict__ Vh, int ldv, int nkeys, int q0, ...
;     ...
;     const int b = j & 1, kt0 = j * KVBLK;
;     const int dlo_ = kt0 - q0 - 255, dhi_ = kt0 + 63 - q0;
;     float cb = 0.f; const bool nearb = !(dlo_ >= 1024) && !(dhi_ <= -1024);
;     if (dlo_ >= 1024) cb = cb_hi; else if (dhi_ <= -1024) cb = cb_lo;
;     const float* tb_ = tbl_l + (kt0 - qlane + TOFF + 4 * hi);
;     f32x16 s0, s1; bf16x8 pa0, pa1, pa2, pa3; float al0, al1;
;     const int vb = vb0 + b * (int)SHM_V;
;     qkt_map_roll<0>(s0, s1, kbA + b * SHM_K, qaA);
;     SBAR();
;     if (nearb) {
.LBB0_335:
	s_add_i32 s6, s61, s11
	s_cmp_lt_i32 s11, s60
	s_cselect_b64 s[8:9], -1, 0
	s_cmpk_gt_i32 s6, 0xfbc1
	s_cselect_b64 s[22:23], -1, 0
	v_cndmask_b32_e64 v227, v197, 0, s[22:23]
	v_cndmask_b32_e64 v227, v207, v227, s[8:9]
	s_and_b32 s64, s62, 0x4000
	v_add_u32_e32 v226, s64, v211
	ds_read_b128 v[2:5], v226 offset:0
	ds_read_b128 v[6:9], v226 offset:0x2000
	v_xor_b32_e32 v144, 32, v226
	ds_read_b128 v[228:231], v144 offset:0
	ds_read_b128 v[232:235], v144 offset:0x2000
	v_sub_f32_e32 v160, v227, v0
	v_mov_b32_e32 v161, v160
	v_mov_b64_e32 v[162:163], v[160:161]
	v_mov_b64_e32 v[164:165], v[160:161]
	v_mov_b64_e32 v[166:167], v[160:161]
	v_mov_b64_e32 v[168:169], v[160:161]
	v_mov_b64_e32 v[170:171], v[160:161]
	v_mov_b64_e32 v[172:173], v[160:161]
	v_mov_b64_e32 v[174:175], v[160:161]
	v_mov_b64_e32 v[144:145], v[160:161]
	v_mov_b64_e32 v[146:147], v[160:161]
	v_mov_b64_e32 v[148:149], v[160:161]
	v_mov_b64_e32 v[150:151], v[160:161]
	v_mov_b64_e32 v[152:153], v[160:161]
	v_mov_b64_e32 v[154:155], v[160:161]
	v_mov_b64_e32 v[156:157], v[160:161]
	v_mov_b64_e32 v[158:159], v[160:161]
	s_waitcnt lgkmcnt(2)
	s_and_b64 s[76:77], s[8:9], s[22:23]
	v_mfma_f32_32x32x16_bf16 v[160:175], v[2:5], v[184:187], v[160:175]
	v_mfma_f32_32x32x16_bf16 v[144:159], v[6:9], v[184:187], v[144:159]
	v_xor_b32_e32 v10, 64, v226
	ds_read_b128 v[2:5], v10 offset:0
	ds_read_b128 v[6:9], v10 offset:0x2000
	ds_read_b128 v[10:13], v208 offset:0x800
	s_waitcnt lgkmcnt(3)
	v_mfma_f32_32x32x16_bf16 v[160:175], v[228:231], v[188:191], v[160:175]
	v_xor_b32_e32 v192, 0x60, v226
	ds_read_b128 v[228:231], v192 offset:0
	v_mfma_f32_32x32x16_bf16 v[144:159], v[232:235], v[188:191], v[144:159]
	ds_read_b128 v[232:235], v192 offset:0x2000
	ds_read_b128 v[236:239], v208 offset:0xc00
	s_waitcnt lgkmcnt(3)
	v_mfma_f32_32x32x16_bf16 v[160:175], v[2:5], v[10:13], v[160:175]
	s_waitcnt lgkmcnt(0)
	v_mfma_f32_32x32x16_bf16 v[144:159], v[6:9], v[10:13], v[144:159]
	v_mfma_f32_32x32x16_bf16 v[160:175], v[228:231], v[236:239], v[160:175]
	v_mfma_f32_32x32x16_bf16 v[144:159], v[232:235], v[236:239], v[144:159]
	v_cndmask_b32_e64 v2, 0, 1, s[76:77]
	v_cmp_ne_u32_e64 s[6:7], 1, v2
	s_andn2_b64 vcc, exec, s[76:77]
	s_cbranch_vccnz .LBB0_337
	v_add_u32_e32 v15, s63, v217
	v_add_u32_e32 v223, 0x15e00, v15
	v_add_u32_e32 v234, 0x15e80, v15
	v_add_u32_e32 v235, 0x15e08, v15
	v_add_u32_e32 v236, 0x15e88, v15
	v_add_u32_e32 v237, 0x15e20, v15
	v_add_u32_e32 v238, 0x15ea0, v15
	v_add_u32_e32 v239, 0x15e28, v15
	v_add_u32_e32 v240, 0x15ea8, v15
	v_add_u32_e32 v228, 0x15e40, v15
	v_add_u32_e32 v229, 0x15ec0, v15
	v_add_u32_e32 v230, 0x15e48, v15
	v_add_u32_e32 v231, 0x15ec8, v15
	v_add_u32_e32 v232, 0x15e60, v15
	v_add_u32_e32 v224, 0x15ee0, v15
	v_add_u32_e32 v233, 0x15e68, v15
	v_add_u32_e32 v225, 0x15ee8, v15
	ds_read2_b32 v[2:3], v223 offset1:1
	ds_read2_b32 v[4:5], v234 offset1:1
	ds_read2_b32 v[6:7], v235 offset1:1
	ds_read2_b32 v[8:9], v236 offset1:1
	ds_read2_b32 v[10:11], v237 offset1:1
	ds_read2_b32 v[12:13], v238 offset1:1
	ds_read2_b32 v[192:193], v239 offset1:1
	ds_read2_b32 v[194:195], v240 offset1:1
	ds_read2_b32 v[202:203], v228 offset1:1
	ds_read2_b32 v[204:205], v229 offset1:1
	ds_read2_b32 v[220:221], v230 offset1:1
	ds_read2_b32 v[242:243], v231 offset1:1
	ds_read2_b32 v[244:245], v232 offset1:1
	ds_read2_b32 v[246:247], v233 offset1:1
	s_waitcnt lgkmcnt(9)
	v_add_f32_e32 v164, v164, v10
	v_add_f32_e32 v165, v165, v11
	v_add_f32_e32 v162, v162, v6
	v_add_f32_e32 v163, v163, v7
	ds_read2_b32 v[6:7], v225 offset1:1
	ds_read2_b32 v[10:11], v224 offset1:1
	s_waitcnt lgkmcnt(9)
	v_add_f32_e32 v166, v166, v192
	v_add_f32_e32 v167, v167, v193
	s_waitcnt lgkmcnt(2)
	v_add_f32_e32 v174, v174, v246
	v_add_f32_e32 v175, v175, v247
	v_add_f32_e32 v172, v172, v244
	v_add_f32_e32 v173, v173, v245
	v_add_f32_e32 v170, v170, v220
	v_add_f32_e32 v171, v171, v221
	v_add_f32_e32 v168, v168, v202
	v_add_f32_e32 v169, v169, v203
	v_add_f32_e32 v160, v160, v2
	v_add_f32_e32 v161, v161, v3
	v_add_f32_e32 v150, v150, v194
	v_add_f32_e32 v151, v151, v195
	v_add_f32_e32 v148, v148, v12
	v_add_f32_e32 v149, v149, v13
	v_add_f32_e32 v146, v146, v8
	v_add_f32_e32 v147, v147, v9
	s_waitcnt lgkmcnt(1)
	v_add_f32_e32 v158, v158, v6
	v_add_f32_e32 v159, v159, v7
	s_waitcnt lgkmcnt(0)
	v_add_f32_e32 v156, v156, v10
	v_add_f32_e32 v157, v157, v11
	v_add_f32_e32 v154, v154, v242
	v_add_f32_e32 v155, v155, v243
	v_add_f32_e32 v152, v152, v204
	v_add_f32_e32 v153, v153, v205
	v_add_f32_e32 v144, v144, v4
	v_add_f32_e32 v145, v145, v5
